# phase 3 chunk tail: group-norm weight loads issued at the tail top, tail waits no longer cover the output stores
# speedup vs baseline: 1.0008x; 1.0008x over previous
.LBB0_422:
	s_or_b64 exec, exec, s[36:37]
	s_waitcnt lgkmcnt(0)
	s_barrier
	v_mov_b32_e32 v232, v156
	v_ashrrev_i32_e32 v233, 31, v156
	v_lshl_add_u64 v[232:233], v[232:233], 0, s[46:47]
	v_lshlrev_b64 v[232:233], 8, v[232:233]
	v_lshl_add_u64 v[232:233], v[150:151], 0, v[232:233]
	global_load_dwordx4 v[216:219], v[232:233], off offset:48
	global_load_dwordx4 v[220:223], v[232:233], off offset:32
	global_load_dwordx4 v[224:227], v[232:233], off offset:16
	global_load_dwordx4 v[228:231], v[232:233], off
	global_load_dwordx4 v[192:195], v[154:155], off offset:16
	global_load_dwordx4 v[196:199], v[154:155], off
	global_load_dwordx4 v[200:203], v[154:155], off offset:48
	global_load_dwordx4 v[204:207], v[154:155], off offset:32
	global_load_dwordx4 v[208:211], v[154:155], off offset:80
	global_load_dwordx4 v[212:215], v[154:155], off offset:64
	global_load_dwordx4 v[236:239], v[154:155], off offset:112
	global_load_dwordx4 v[240:243], v[154:155], off offset:96
	ds_read_b128 v[0:3], v167
	ds_read_b128 v[4:7], v167 offset:416
	ds_read_b128 v[8:11], v167 offset:448
	v_add_u32_e32 v157, v170, v179
	s_add_u32 s52, s52, 0x4000
	s_waitcnt lgkmcnt(2)
	v_pk_mul_f32 v[48:49], v[108:109], v[0:1]
	v_pk_mul_f32 v[50:51], v[114:115], v[2:3]
	ds_read_b128 v[0:3], v167 offset:32
	ds_read_b128 v[12:15], v167 offset:480
	v_cvt_pk_bf16_f32 v64, v48, v49
	v_cvt_pk_bf16_f32 v65, v50, v51
	s_waitcnt lgkmcnt(3)
	v_pk_mul_f32 v[4:5], v[144:145], v[4:5]
	s_waitcnt lgkmcnt(1)
	v_pk_mul_f32 v[52:53], v[52:53], v[0:1]
	v_pk_mul_f32 v[54:55], v[54:55], v[2:3]
	ds_read_b128 v[0:3], v167 offset:64
	v_cvt_pk_bf16_f32 v66, v52, v53
	v_cvt_pk_bf16_f32 v67, v54, v55
	v_pk_mul_f32 v[6:7], v[138:139], v[6:7]
	v_pk_mul_f32 v[8:9], v[146:147], v[8:9]
	s_waitcnt lgkmcnt(0)
	v_pk_mul_f32 v[56:57], v[56:57], v[0:1]
	v_pk_mul_f32 v[58:59], v[58:59], v[2:3]
	ds_read_b128 v[0:3], v167 offset:96
	v_pk_mul_f32 v[10:11], v[140:141], v[10:11]
	v_pk_mul_f32 v[12:13], v[148:149], v[12:13]
	v_pk_mul_f32 v[14:15], v[142:143], v[14:15]
	s_addc_u32 s53, s53, 0
	s_waitcnt lgkmcnt(0)
	v_pk_mul_f32 v[60:61], v[60:61], v[0:1]
	v_pk_mul_f32 v[62:63], v[62:63], v[2:3]
	ds_read_b128 v[0:3], v167 offset:128
	s_cmp_eq_u32 s52, 0x20000
	s_waitcnt lgkmcnt(0)
	v_pk_mul_f32 v[32:33], v[100:101], v[0:1]
	v_pk_mul_f32 v[34:35], v[96:97], v[2:3]
	ds_read_b128 v[0:3], v167 offset:160
	v_cvt_pk_bf16_f32 v100, v56, v57
	v_cvt_pk_bf16_f32 v101, v58, v59
	s_waitcnt lgkmcnt(0)
	v_pk_mul_f32 v[36:37], v[110:111], v[0:1]
	v_pk_mul_f32 v[38:39], v[102:103], v[2:3]
	ds_read_b128 v[0:3], v167 offset:192
	v_cvt_pk_bf16_f32 v102, v60, v61
	v_cvt_pk_bf16_f32 v103, v62, v63
	s_waitcnt lgkmcnt(0)
	v_pk_mul_f32 v[40:41], v[104:105], v[0:1]
	v_pk_mul_f32 v[42:43], v[98:99], v[2:3]
	ds_read_b128 v[0:3], v167 offset:224
	v_add_u32_e32 v104, 0x2000, v180
	s_waitcnt lgkmcnt(0)
	v_pk_mul_f32 v[44:45], v[116:117], v[0:1]
	v_pk_mul_f32 v[46:47], v[106:107], v[2:3]
	ds_read_b128 v[0:3], v167 offset:256
	s_waitcnt lgkmcnt(0)
	v_pk_mul_f32 v[16:17], v[122:123], v[0:1]
	v_pk_mul_f32 v[18:19], v[118:119], v[2:3]
	ds_read_b128 v[0:3], v167 offset:288
	s_waitcnt lgkmcnt(0)
	v_pk_mul_f32 v[20:21], v[130:131], v[0:1]
	v_pk_mul_f32 v[22:23], v[124:125], v[2:3]
	ds_read_b128 v[0:3], v167 offset:320
	s_waitcnt lgkmcnt(0)
	v_pk_mul_f32 v[24:25], v[126:127], v[0:1]
	v_pk_mul_f32 v[26:27], v[120:121], v[2:3]
	ds_read_b128 v[0:3], v167 offset:352
	s_waitcnt lgkmcnt(0)
	v_pk_mul_f32 v[28:29], v[132:133], v[0:1]
	v_pk_mul_f32 v[30:31], v[128:129], v[2:3]
	ds_read_b128 v[0:3], v167 offset:384
	ds_read2_b64 v[68:71], v180 offset1:2
	ds_read2_b64 v[96:99], v180 offset0:4 offset1:6
	s_waitcnt lgkmcnt(1)
	v_mfma_f32_32x32x16_bf16 v[80:95], v[64:67], v[68:71], 0
	ds_read2_b64 v[68:71], v104 offset0:64 offset1:66
	v_mul_f32_e64 v0, v136, v0
	v_mul_f32_e64 v1, v137, v1
	v_mul_f32_e64 v2, v134, v2
	v_mul_f32_e64 v3, v135, v3
	s_waitcnt lgkmcnt(0)
	v_mfma_f32_32x32x16_bf16 v[64:79], v[64:67], v[68:71], 0
	v_mfma_f32_32x32x16_bf16 v[80:95], v[100:103], v[96:99], v[80:95]
	ds_read2_b64 v[96:99], v104 offset0:68 offset1:70
	s_waitcnt lgkmcnt(0)
	v_mfma_f32_32x32x16_bf16 v[64:79], v[100:103], v[96:99], v[64:79]
	v_cvt_pk_bf16_f32 v96, v32, v33
	v_cvt_pk_bf16_f32 v97, v34, v35
	v_cvt_pk_bf16_f32 v98, v36, v37
	v_cvt_pk_bf16_f32 v99, v38, v39
	ds_read2_b64 v[100:103], v180 offset0:8 offset1:10
	s_waitcnt lgkmcnt(0)
	v_mfma_f32_32x32x16_bf16 v[80:95], v[96:99], v[100:103], v[80:95]
	ds_read2_b64 v[100:103], v104 offset0:72 offset1:74
	s_waitcnt lgkmcnt(0)
	v_mfma_f32_32x32x16_bf16 v[64:79], v[96:99], v[100:103], v[64:79]
	v_cvt_pk_bf16_f32 v96, v40, v41
	v_cvt_pk_bf16_f32 v97, v42, v43
	v_cvt_pk_bf16_f32 v98, v44, v45
	v_cvt_pk_bf16_f32 v99, v46, v47
	ds_read2_b64 v[100:103], v180 offset0:12 offset1:14
	s_waitcnt lgkmcnt(0)
	v_mfma_f32_32x32x16_bf16 v[80:95], v[96:99], v[100:103], v[80:95]
	ds_read2_b64 v[100:103], v104 offset0:76 offset1:78
	s_waitcnt lgkmcnt(0)
	v_mfma_f32_32x32x16_bf16 v[64:79], v[96:99], v[100:103], v[64:79]
	v_cvt_pk_bf16_f32 v96, v16, v17
	v_cvt_pk_bf16_f32 v97, v18, v19
	v_cvt_pk_bf16_f32 v98, v20, v21
	v_cvt_pk_bf16_f32 v99, v22, v23
	ds_read2_b64 v[100:103], v180 offset0:16 offset1:18
	s_waitcnt lgkmcnt(0)
	v_mfma_f32_32x32x16_bf16 v[80:95], v[96:99], v[100:103], v[80:95]
	ds_read2_b64 v[100:103], v104 offset0:80 offset1:82
	s_waitcnt lgkmcnt(0)
	v_mfma_f32_32x32x16_bf16 v[64:79], v[96:99], v[100:103], v[64:79]
	v_cvt_pk_bf16_f32 v96, v24, v25
	v_cvt_pk_bf16_f32 v97, v26, v27
	v_cvt_pk_bf16_f32 v98, v28, v29
	v_cvt_pk_bf16_f32 v99, v30, v31
	ds_read2_b64 v[100:103], v180 offset0:20 offset1:22
	s_waitcnt lgkmcnt(0)
	v_mfma_f32_32x32x16_bf16 v[80:95], v[96:99], v[100:103], v[80:95]
	ds_read2_b64 v[100:103], v104 offset0:84 offset1:86
	s_waitcnt lgkmcnt(0)
	v_mfma_f32_32x32x16_bf16 v[64:79], v[96:99], v[100:103], v[64:79]
	v_cvt_pk_bf16_f32 v96, v0, v1
	v_cvt_pk_bf16_f32 v97, v2, v3
	v_cvt_pk_bf16_f32 v98, v4, v5
	v_cvt_pk_bf16_f32 v99, v6, v7
	ds_read2_b64 v[100:103], v180 offset0:24 offset1:26
	s_waitcnt lgkmcnt(0)
	v_mfma_f32_32x32x16_bf16 v[80:95], v[96:99], v[100:103], v[80:95]
	ds_read2_b64 v[100:103], v104 offset0:88 offset1:90
	s_waitcnt lgkmcnt(0)
	v_mfma_f32_32x32x16_bf16 v[64:79], v[96:99], v[100:103], v[64:79]
	v_cvt_pk_bf16_f32 v96, v8, v9
	v_cvt_pk_bf16_f32 v97, v10, v11
	v_cvt_pk_bf16_f32 v98, v12, v13
	v_cvt_pk_bf16_f32 v99, v14, v15
	ds_read2_b64 v[100:103], v180 offset0:28 offset1:30
	s_waitcnt lgkmcnt(0)
	v_mfma_f32_32x32x16_bf16 v[80:95], v[96:99], v[100:103], v[80:95]
	ds_read2_b64 v[100:103], v104 offset0:92 offset1:94
	s_waitcnt lgkmcnt(0)
	v_mfma_f32_32x32x16_bf16 v[64:79], v[96:99], v[100:103], v[64:79]
	ds_read_b128 v[114:117], v157 offset:17408
	ds_read_b128 v[96:99], v157
	ds_read_b128 v[118:121], v157 offset:32
	ds_read_b128 v[122:125], v157 offset:17440
	s_waitcnt lgkmcnt(2)
	v_mfma_f32_32x32x16_bf16 v[96:111], v[114:117], v[96:99], 0
	s_waitcnt lgkmcnt(0)
	v_mfma_f32_32x32x16_bf16 v[96:111], v[122:125], v[118:121], v[96:111]
	ds_read_b128 v[118:121], v157 offset:17472
	ds_read_b128 v[126:129], v157 offset:64
	s_waitcnt lgkmcnt(0)
	v_mfma_f32_32x32x16_bf16 v[96:111], v[118:121], v[126:129], v[96:111]
	ds_read_b128 v[126:129], v157 offset:17504
	ds_read_b128 v[130:133], v157 offset:96
	s_waitcnt lgkmcnt(0)
	v_mfma_f32_32x32x16_bf16 v[96:111], v[126:129], v[130:133], v[96:111]
	ds_read_b128 v[130:133], v157 offset:17536
	ds_read_b128 v[134:137], v157 offset:128
	s_waitcnt lgkmcnt(0)
	v_mfma_f32_32x32x16_bf16 v[96:111], v[130:133], v[134:137], v[96:111]
	ds_read_b128 v[134:137], v157 offset:17568
	ds_read_b128 v[138:141], v157 offset:160
	s_waitcnt lgkmcnt(0)
	v_mfma_f32_32x32x16_bf16 v[96:111], v[134:137], v[138:141], v[96:111]
	ds_read_b128 v[138:141], v157 offset:17600
	ds_read_b128 v[142:145], v157 offset:192
	s_waitcnt lgkmcnt(0)
	v_mfma_f32_32x32x16_bf16 v[96:111], v[138:141], v[142:145], v[96:111]
	ds_read_b128 v[142:145], v157 offset:17632
	ds_read_b128 v[146:149], v157 offset:224
	s_waitcnt lgkmcnt(0)
	v_mfma_f32_32x32x16_bf16 v[96:111], v[142:145], v[146:149], v[96:111]
	s_nop 11
	v_cndmask_b32_e64 v146, v96, 0, s[34:35]
	v_cndmask_b32_e64 v96, v146, v96, s[30:31]
	v_cndmask_b32_e64 v97, 0, v97, s[30:31]
	v_cndmask_b32_e64 v98, v98, 0, s[28:29]
	v_cndmask_b32_e64 v99, v99, 0, s[26:27]
	v_cndmask_b32_e64 v100, v100, 0, s[24:25]
	v_cndmask_b32_e64 v101, v101, 0, s[22:23]
	v_cvt_pk_bf16_f32 v96, v96, v97
	v_cvt_pk_bf16_f32 v97, v98, v99
	v_cvt_pk_bf16_f32 v98, v100, v101
	v_add_u32_e32 v100, v171, v168
	v_add_u32_e32 v183, 0xd000, v100
	ds_read2_b64 v[146:149], v183 offset1:2
	ds_read2_b64 v[184:187], v183 offset0:4 offset1:6
	v_cndmask_b32_e64 v102, v102, 0, s[20:21]
	v_cndmask_b32_e64 v103, v103, 0, s[18:19]
	v_cvt_pk_bf16_f32 v99, v102, v103
	ds_read_b128 v[188:191], v157 offset:8704
	v_cndmask_b32_e64 v104, v104, 0, s[16:17]
	s_waitcnt lgkmcnt(2)
	v_mfma_f32_32x32x16_bf16 v[80:95], v[146:149], v[96:99], v[80:95]
	v_cndmask_b32_e64 v105, v105, 0, s[14:15]
	v_cndmask_b32_e64 v106, v106, 0, s[12:13]
	v_cndmask_b32_e64 v107, v107, 0, s[10:11]
	v_cndmask_b32_e64 v108, v108, 0, s[8:9]
	v_cndmask_b32_e64 v109, v109, 0, s[6:7]
	v_cndmask_b32_e64 v110, v110, 0, s[4:5]
	v_cndmask_b32_e64 v111, v111, 0, s[2:3]
	v_cvt_pk_bf16_f32 v96, v104, v105
	v_cvt_pk_bf16_f32 v97, v106, v107
	v_cvt_pk_bf16_f32 v98, v108, v109
	v_cvt_pk_bf16_f32 v99, v110, v111
	s_waitcnt lgkmcnt(1)
	s_nop 0
	v_mfma_f32_32x32x16_bf16 v[80:95], v[184:187], v[96:99], v[80:95]
	s_waitcnt lgkmcnt(0)
	v_mfma_f32_32x32x16_bf16 v[96:111], v[114:117], v[188:191], 0
	ds_read_b128 v[114:117], v157 offset:8736
	s_waitcnt lgkmcnt(0)
	v_mfma_f32_32x32x16_bf16 v[96:111], v[122:125], v[114:117], v[96:111]
	ds_read_b128 v[122:125], v157 offset:8768
	s_waitcnt lgkmcnt(0)
	v_mfma_f32_32x32x16_bf16 v[96:111], v[118:121], v[122:125], v[96:111]
	ds_read_b128 v[118:121], v157 offset:8800
	s_waitcnt lgkmcnt(0)
	v_mfma_f32_32x32x16_bf16 v[96:111], v[126:129], v[118:121], v[96:111]
	ds_read_b128 v[126:129], v157 offset:8832
	s_waitcnt lgkmcnt(0)
	v_mfma_f32_32x32x16_bf16 v[96:111], v[130:133], v[126:129], v[96:111]
	ds_read_b128 v[130:133], v157 offset:8864
	s_waitcnt lgkmcnt(0)
	v_mfma_f32_32x32x16_bf16 v[96:111], v[134:137], v[130:133], v[96:111]
	ds_read_b128 v[134:137], v157 offset:8896
	s_waitcnt lgkmcnt(0)
	v_mfma_f32_32x32x16_bf16 v[96:111], v[138:141], v[134:137], v[96:111]
	ds_read_b128 v[138:141], v157 offset:8928
	s_waitcnt lgkmcnt(0)
	v_mfma_f32_32x32x16_bf16 v[96:111], v[142:145], v[138:141], v[96:111]
	ds_read_b128 v[142:145], v157 offset:26144
	s_nop 10
	v_cvt_pk_bf16_f32 v96, v96, v97
	v_cvt_pk_bf16_f32 v97, v98, v99
	v_cvt_pk_bf16_f32 v98, v100, v101
	v_cvt_pk_bf16_f32 v99, v102, v103
	s_nop 1
	v_mfma_f32_32x32x16_bf16 v[64:79], v[146:149], v[96:99], v[64:79]
	v_cvt_pk_bf16_f32 v96, v104, v105
	v_cvt_pk_bf16_f32 v97, v106, v107
	v_cvt_pk_bf16_f32 v98, v108, v109
	v_cvt_pk_bf16_f32 v99, v110, v111
	s_nop 1
	v_mfma_f32_32x32x16_bf16 v[64:79], v[184:187], v[96:99], v[64:79]
	ds_read_b128 v[96:99], v157 offset:26112
	s_waitcnt lgkmcnt(0)
	v_mfma_f32_32x32x16_bf16 v[96:111], v[96:99], v[188:191], 0
	v_mfma_f32_32x32x16_bf16 v[96:111], v[142:145], v[114:117], v[96:111]
	ds_read_b128 v[114:117], v157 offset:26176
	s_waitcnt lgkmcnt(0)
	v_mfma_f32_32x32x16_bf16 v[96:111], v[114:117], v[122:125], v[96:111]
	ds_read_b128 v[114:117], v157 offset:26208
	s_waitcnt lgkmcnt(0)
	v_mfma_f32_32x32x16_bf16 v[96:111], v[114:117], v[118:121], v[96:111]
	ds_read_b128 v[114:117], v157 offset:26240
	s_waitcnt lgkmcnt(0)
	v_mfma_f32_32x32x16_bf16 v[96:111], v[114:117], v[126:129], v[96:111]
	ds_read_b128 v[114:117], v157 offset:26272
	s_waitcnt lgkmcnt(0)
	v_mfma_f32_32x32x16_bf16 v[96:111], v[114:117], v[130:133], v[96:111]
	ds_read_b128 v[114:117], v157 offset:26304
	s_waitcnt lgkmcnt(0)
	v_mfma_f32_32x32x16_bf16 v[96:111], v[114:117], v[134:137], v[96:111]
	ds_read_b128 v[114:117], v157 offset:26336
	v_ashrrev_i32_e32 v157, 31, v156
	s_waitcnt lgkmcnt(0)
	v_mfma_f32_32x32x16_bf16 v[96:111], v[114:117], v[138:141], v[96:111]
	s_nop 11
	v_cndmask_b32_e64 v114, v96, 0, s[34:35]
	v_cndmask_b32_e64 v96, v114, v96, s[30:31]
	v_cndmask_b32_e64 v97, 0, v97, s[30:31]
	v_cndmask_b32_e64 v98, v98, 0, s[28:29]
	v_cndmask_b32_e64 v99, v99, 0, s[26:27]
	v_cndmask_b32_e64 v100, v100, 0, s[24:25]
	v_cndmask_b32_e64 v101, v101, 0, s[22:23]
	v_cndmask_b32_e64 v102, v102, 0, s[20:21]
	v_cndmask_b32_e64 v103, v103, 0, s[18:19]
	v_cvt_pk_bf16_f32 v96, v96, v97
	v_cvt_pk_bf16_f32 v97, v98, v99
	v_cvt_pk_bf16_f32 v98, v100, v101
	v_cvt_pk_bf16_f32 v99, v102, v103
	ds_read2_b64 v[100:103], v183 offset0:8 offset1:10
	v_cndmask_b32_e64 v104, v104, 0, s[16:17]
	s_waitcnt lgkmcnt(0)
	v_mfma_f32_32x32x16_bf16 v[64:79], v[100:103], v[96:99], v[64:79]
	ds_read2_b64 v[100:103], v183 offset0:12 offset1:14
	v_cndmask_b32_e64 v105, v105, 0, s[14:15]
	v_cndmask_b32_e64 v106, v106, 0, s[12:13]
	v_cndmask_b32_e64 v107, v107, 0, s[10:11]
	v_cndmask_b32_e64 v108, v108, 0, s[8:9]
	v_cndmask_b32_e64 v109, v109, 0, s[6:7]
	v_cndmask_b32_e64 v110, v110, 0, s[4:5]
	v_cndmask_b32_e64 v111, v111, 0, s[2:3]
	v_cvt_pk_bf16_f32 v96, v104, v105
	v_cvt_pk_bf16_f32 v97, v106, v107
	v_cvt_pk_bf16_f32 v98, v108, v109
	v_cvt_pk_bf16_f32 v99, v110, v111
	v_add_u32_e32 v108, v171, v169
	s_waitcnt lgkmcnt(0)
	v_mfma_f32_32x32x16_bf16 v[64:79], v[100:103], v[96:99], v[64:79]
	ds_read_b128 v[96:99], v108 offset:53248
	ds_read_b128 v[100:103], v108 offset:53280
	ds_read_b128 v[104:107], v108 offset:53312
	ds_read_b128 v[108:111], v108 offset:53344
	ds_read_b128 v[114:117], v181 offset:34816
	ds_read_b128 v[118:121], v181 offset:34848
	s_waitcnt lgkmcnt(1)
	v_mfma_f32_32x32x16_bf16 v[48:63], v[114:117], v[96:99], v[48:63]
	ds_read_b128 v[114:117], v181 offset:34880
	s_waitcnt lgkmcnt(1)
	v_mfma_f32_32x32x16_bf16 v[48:63], v[118:121], v[100:103], v[48:63]
	s_waitcnt lgkmcnt(0)
	v_mfma_f32_32x32x16_bf16 v[48:63], v[114:117], v[104:107], v[48:63]
	ds_read_b128 v[114:117], v181 offset:34912
	s_waitcnt lgkmcnt(0)
	v_mfma_f32_32x32x16_bf16 v[48:63], v[114:117], v[108:111], v[48:63]
	ds_read_b128 v[114:117], v181 offset:39424
	s_waitcnt lgkmcnt(0)
	v_mfma_f32_32x32x16_bf16 v[32:47], v[114:117], v[96:99], v[32:47]
	ds_read_b128 v[114:117], v181 offset:39456
	s_waitcnt lgkmcnt(0)
	v_mfma_f32_32x32x16_bf16 v[32:47], v[114:117], v[100:103], v[32:47]
	ds_read_b128 v[114:117], v181 offset:39488
	s_waitcnt lgkmcnt(0)
	v_mfma_f32_32x32x16_bf16 v[32:47], v[114:117], v[104:107], v[32:47]
	ds_read_b128 v[114:117], v181 offset:39520
	s_waitcnt lgkmcnt(0)
	v_mfma_f32_32x32x16_bf16 v[32:47], v[114:117], v[108:111], v[32:47]
	ds_read_b128 v[114:117], v181 offset:44032
	s_waitcnt lgkmcnt(0)
	v_mfma_f32_32x32x16_bf16 v[16:31], v[114:117], v[96:99], v[16:31]
	ds_read_b128 v[114:117], v181 offset:44064
	s_waitcnt lgkmcnt(0)
	v_mfma_f32_32x32x16_bf16 v[16:31], v[114:117], v[100:103], v[16:31]
	ds_read_b128 v[114:117], v181 offset:44096
	s_waitcnt lgkmcnt(0)
	v_mfma_f32_32x32x16_bf16 v[16:31], v[114:117], v[104:107], v[16:31]
	ds_read_b128 v[114:117], v181 offset:44128
	s_waitcnt lgkmcnt(0)
	v_mfma_f32_32x32x16_bf16 v[16:31], v[114:117], v[108:111], v[16:31]
	ds_read_b128 v[114:117], v181 offset:48640
	s_waitcnt lgkmcnt(0)
	v_mfma_f32_32x32x16_bf16 v[0:15], v[114:117], v[96:99], v[0:15]
	ds_read_b128 v[96:99], v181 offset:48672
	s_waitcnt lgkmcnt(0)
	v_mfma_f32_32x32x16_bf16 v[0:15], v[96:99], v[100:103], v[0:15]
	ds_read_b128 v[96:99], v181 offset:48704
	s_waitcnt lgkmcnt(0)
	v_mfma_f32_32x32x16_bf16 v[0:15], v[96:99], v[104:107], v[0:15]
	ds_read_b128 v[96:99], v181 offset:48736
	s_waitcnt lgkmcnt(0)
	v_mfma_f32_32x32x16_bf16 v[0:15], v[96:99], v[108:111], v[0:15]
	ds_read_b128 v[96:99], v172
	ds_read_b128 v[100:103], v172 offset:32
	s_waitcnt lgkmcnt(1)
	v_mul_f32_e64 v108, v48, v96
	v_mul_f32_e64 v109, v49, v97
	v_pk_mul_f32 v[114:115], v[50:51], v[98:99]
	ds_read_b128 v[48:51], v172 offset:64
	s_waitcnt lgkmcnt(1)
	v_pk_mul_f32 v[52:53], v[52:53], v[100:101]
	v_pk_mul_f32 v[54:55], v[54:55], v[102:103]
	s_waitcnt lgkmcnt(0)
	v_pk_mul_f32 v[56:57], v[56:57], v[48:49]
	v_pk_mul_f32 v[58:59], v[58:59], v[50:51]
	ds_read_b128 v[48:51], v172 offset:96
	s_waitcnt lgkmcnt(0)
	v_pk_mul_f32 v[60:61], v[60:61], v[48:49]
	v_pk_mul_f32 v[62:63], v[62:63], v[50:51]
	ds_read_b128 v[48:51], v172 offset:128
	s_waitcnt lgkmcnt(0)
	v_pk_mul_f32 v[100:101], v[32:33], v[48:49]
	v_pk_mul_f32 v[96:97], v[34:35], v[50:51]
	ds_read_b128 v[32:35], v172 offset:160
	s_waitcnt lgkmcnt(0)
	v_pk_mul_f32 v[110:111], v[36:37], v[32:33]
	v_pk_mul_f32 v[102:103], v[38:39], v[34:35]
	ds_read_b128 v[32:35], v172 offset:192
	s_waitcnt lgkmcnt(0)
	v_pk_mul_f32 v[104:105], v[40:41], v[32:33]
	v_pk_mul_f32 v[98:99], v[42:43], v[34:35]
	ds_read_b128 v[32:35], v172 offset:224
	s_waitcnt lgkmcnt(0)
	v_pk_mul_f32 v[116:117], v[44:45], v[32:33]
	v_pk_mul_f32 v[106:107], v[46:47], v[34:35]
	ds_read_b128 v[32:35], v172 offset:256
	s_waitcnt lgkmcnt(0)
	v_pk_mul_f32 v[122:123], v[16:17], v[32:33]
	v_pk_mul_f32 v[118:119], v[18:19], v[34:35]
	ds_read_b128 v[16:19], v172 offset:288
	s_waitcnt lgkmcnt(0)
	v_pk_mul_f32 v[130:131], v[20:21], v[16:17]
	v_pk_mul_f32 v[124:125], v[22:23], v[18:19]
	ds_read_b128 v[16:19], v172 offset:320
	s_waitcnt lgkmcnt(0)
	v_pk_mul_f32 v[126:127], v[24:25], v[16:17]
	v_pk_mul_f32 v[120:121], v[26:27], v[18:19]
	ds_read_b128 v[16:19], v172 offset:352
	s_waitcnt lgkmcnt(0)
	v_pk_mul_f32 v[132:133], v[28:29], v[16:17]
	v_pk_mul_f32 v[128:129], v[30:31], v[18:19]
	ds_read_b128 v[16:19], v172 offset:384
	v_lshlrev_b64 v[30:31], 12, v[156:157]
	s_waitcnt lgkmcnt(0)
	v_pk_mul_f32 v[136:137], v[0:1], v[16:17]
	v_pk_mul_f32 v[134:135], v[2:3], v[18:19]
	ds_read_b128 v[0:3], v172 offset:416
	s_waitcnt lgkmcnt(0)
	v_pk_mul_f32 v[144:145], v[4:5], v[0:1]
	v_pk_mul_f32 v[138:139], v[6:7], v[2:3]
	ds_read_b128 v[0:3], v172 offset:448
	s_waitcnt lgkmcnt(0)
	v_pk_mul_f32 v[146:147], v[8:9], v[0:1]
	v_pk_mul_f32 v[140:141], v[10:11], v[2:3]
	ds_read_b128 v[0:3], v172 offset:480
	s_waitcnt lgkmcnt(0)
	s_barrier
	ds_write_b128 v182, v[80:83]
	ds_write_b128 v182, v[84:87] offset:32
	ds_write_b128 v182, v[88:91] offset:64
	ds_write_b128 v182, v[92:95] offset:96
	ds_write_b128 v182, v[64:67] offset:16896
	ds_write_b128 v182, v[68:71] offset:16928
	ds_write_b128 v182, v[72:75] offset:16960
	ds_write_b128 v182, v[76:79] offset:16992
	v_pk_mul_f32 v[148:149], v[12:13], v[0:1]
	v_pk_mul_f32 v[142:143], v[14:15], v[2:3]
	s_waitcnt lgkmcnt(0)
	s_barrier
	ds_read_b128 v[16:19], v173 offset:64
	ds_read_b128 v[12:15], v173 offset:80
	v_lshl_add_u64 v[64:65], v[152:153], 0, v[30:31]
	s_waitcnt lgkmcnt(1)
	v_pk_mul_f32 v[4:5], v[16:17], v[16:17]
	s_waitcnt lgkmcnt(0)
	v_pk_mul_f32 v[6:7], v[12:13], v[12:13]
	v_pk_mul_f32 v[0:1], v[18:19], v[18:19]
	v_pk_mul_f32 v[2:3], v[14:15], v[14:15]
	v_mov_b32_e32 v8, v4
	v_mov_b32_e32 v9, v6
	v_mov_b32_e32 v6, v5
	v_pk_add_f32 v[4:5], v[8:9], v[6:7]
	v_mov_b32_e32 v6, v0
	v_mov_b32_e32 v7, v2
	v_pk_add_f32 v[4:5], v[4:5], v[6:7]
	v_mov_b32_e32 v2, v1
	v_pk_add_f32 v[66:67], v[4:5], v[2:3]
	ds_read_b128 v[4:7], v173 offset:96
	ds_read_b128 v[0:3], v173 offset:112
	s_waitcnt lgkmcnt(1)
	v_pk_mul_f32 v[20:21], v[4:5], v[4:5]
	s_waitcnt lgkmcnt(0)
	v_pk_mul_f32 v[22:23], v[0:1], v[0:1]
	v_pk_mul_f32 v[8:9], v[6:7], v[6:7]
	v_pk_mul_f32 v[10:11], v[2:3], v[2:3]
	v_mov_b32_e32 v24, v20
	v_mov_b32_e32 v25, v22
	v_mov_b32_e32 v22, v21
	v_pk_add_f32 v[20:21], v[24:25], v[22:23]
	v_mov_b32_e32 v22, v8
	v_mov_b32_e32 v23, v10
	v_mov_b32_e32 v10, v9
	v_lshl_add_u64 v[8:9], v[156:157], 0, s[46:47]
	v_lshlrev_b64 v[8:9], 8, v[8:9]
	v_pk_add_f32 v[20:21], v[20:21], v[22:23]
	v_lshl_add_u64 v[28:29], v[150:151], 0, v[8:9]
	v_pk_add_f32 v[68:69], v[20:21], v[10:11]
	ds_read_b128 v[48:51], v173
	ds_read_b128 v[40:43], v173 offset:16
	ds_read_b128 v[32:35], v173 offset:32
	ds_read_b128 v[28:31], v173 offset:48
	s_waitcnt lgkmcnt(3)
	v_mov_b32_e32 v84, v49
	s_waitcnt lgkmcnt(2)
	v_mov_b32_e32 v85, v41
	v_mov_b32_e32 v78, v48
	v_mov_b32_e32 v79, v40
	v_pk_mul_f32 v[84:85], v[84:85], v[84:85]
	s_waitcnt lgkmcnt(1)
	v_mov_b32_e32 v90, v33
	v_pk_fma_f32 v[78:79], v[78:79], v[78:79], v[84:85]
	s_waitcnt lgkmcnt(0)
	v_mov_b32_e32 v91, v29
	v_mov_b32_e32 v74, v51
	v_mov_b32_e32 v75, v43
	v_mov_b32_e32 v88, v32
	v_mov_b32_e32 v89, v28
	v_pk_mul_f32 v[90:91], v[90:91], v[90:91]
	v_mov_b32_e32 v86, v35
	v_pk_fma_f32 v[88:89], v[88:89], v[88:89], v[90:91]
	v_mov_b32_e32 v87, v31
	v_add_u32_e32 v156, 64, v156
	s_waitcnt vmcnt(8)
	v_lshlrev_b32_e32 v80, 16, v229
	v_and_b32_e32 v81, 0xffff0000, v229
	v_lshlrev_b32_e32 v82, 16, v228
	v_and_b32_e32 v83, 0xffff0000, v228
	v_mov_b32_e32 v70, v50
	v_mov_b32_e32 v71, v42
	v_pk_fma_f32 v[70:71], v[70:71], v[70:71], v[78:79]
	v_lshlrev_b32_e32 v76, 16, v230
	v_and_b32_e32 v77, 0xffff0000, v230
	v_pk_fma_f32 v[84:85], v[74:75], v[74:75], v[70:71]
	v_lshlrev_b32_e32 v78, 16, v231
	v_and_b32_e32 v79, 0xffff0000, v231
	v_lshlrev_b32_e32 v72, 16, v225
	v_and_b32_e32 v73, 0xffff0000, v225
	v_lshlrev_b32_e32 v74, 16, v224
	v_and_b32_e32 v75, 0xffff0000, v224
	v_mov_b32_e32 v24, v34
	v_mov_b32_e32 v25, v30
	v_pk_fma_f32 v[24:25], v[24:25], v[24:25], v[88:89]
	v_lshlrev_b32_e32 v70, 16, v226
	v_and_b32_e32 v71, 0xffff0000, v226
	v_pk_fma_f32 v[24:25], v[86:87], v[86:87], v[24:25]
	v_add_f32_e32 v26, v84, v85
	v_add_f32_e32 v24, v26, v24
	v_add_f32_e32 v24, v24, v25
	v_add_f32_e32 v24, v24, v66
	v_add_f32_e32 v24, v24, v67
	v_add_f32_e32 v24, v24, v68
	v_add_f32_e32 v24, v24, v69
	ds_bpermute_b32 v25, v174, v24
	v_lshlrev_b32_e32 v26, 16, v227
	v_and_b32_e32 v27, 0xffff0000, v227
	s_waitcnt lgkmcnt(0)
	v_add_f32_e32 v24, v24, v25
	ds_bpermute_b32 v25, v175, v24
	s_waitcnt lgkmcnt(0)
	v_add_f32_e32 v24, v24, v25
	v_fmamk_f32 v24, v24, 0x3c000000, v161
	v_cmp_gt_f32_e64 s[36:37], s70, v24
	v_mul_f32_e32 v25, 0x4b800000, v24
	s_nop 0
	v_cndmask_b32_e64 v24, v24, v25, s[36:37]
	v_rsq_f32_e32 v24, v24
	s_nop 0
	v_mul_f32_e32 v25, 0x45800000, v24
	v_cndmask_b32_e64 v24, v24, v25, s[36:37]
	v_pk_mul_f32 v[48:49], v[48:49], v[24:25] op_sel_hi:[1,0]
	v_pk_mul_f32 v[40:41], v[40:41], v[24:25] op_sel_hi:[1,0]
	s_waitcnt vmcnt(6)
	v_pk_mul_f32 v[44:45], v[196:197], v[48:49]
	v_pk_mul_f32 v[48:49], v[50:51], v[24:25] op_sel_hi:[1,0]
	v_pk_mul_f32 v[36:37], v[192:193], v[40:41]
	v_pk_mul_f32 v[46:47], v[198:199], v[48:49]
	v_pk_mul_f32 v[44:45], v[44:45], v[82:83]
	v_pk_mul_f32 v[46:47], v[46:47], v[80:81]
	v_pk_mul_f32 v[36:37], v[36:37], v[76:77]
	v_cvt_pk_bf16_f32 v44, v44, v45
	v_cvt_pk_bf16_f32 v45, v46, v47
	v_cvt_pk_bf16_f32 v46, v36, v37
	v_pk_mul_f32 v[36:37], v[42:43], v[24:25] op_sel_hi:[1,0]
	v_pk_mul_f32 v[32:33], v[32:33], v[24:25] op_sel_hi:[1,0]
	v_pk_mul_f32 v[36:37], v[36:37], v[194:195]
	v_pk_mul_f32 v[34:35], v[34:35], v[24:25] op_sel_hi:[1,0]
	v_pk_mul_f32 v[36:37], v[36:37], v[78:79]
	v_pk_mul_f32 v[28:29], v[28:29], v[24:25] op_sel_hi:[1,0]
	v_cvt_pk_bf16_f32 v47, v36, v37
	global_store_dwordx4 v[64:65], v[44:47], off
	v_pk_mul_f32 v[16:17], v[16:17], v[24:25] op_sel_hi:[1,0]
	v_pk_mul_f32 v[18:19], v[18:19], v[24:25] op_sel_hi:[1,0]
	v_pk_mul_f32 v[12:13], v[12:13], v[24:25] op_sel_hi:[1,0]
	v_pk_mul_f32 v[4:5], v[4:5], v[24:25] op_sel_hi:[1,0]
	v_pk_mul_f32 v[6:7], v[6:7], v[24:25] op_sel_hi:[1,0]
	v_pk_mul_f32 v[0:1], v[0:1], v[24:25] op_sel_hi:[1,0]
	s_waitcnt vmcnt(5)
	v_pk_mul_f32 v[28:29], v[28:29], v[200:201]
	s_nop 0
	v_pk_mul_f32 v[32:33], v[32:33], v[204:205]
	v_pk_mul_f32 v[34:35], v[34:35], v[206:207]
	v_pk_mul_f32 v[32:33], v[32:33], v[74:75]
	v_pk_mul_f32 v[34:35], v[34:35], v[72:73]
	v_pk_mul_f32 v[28:29], v[28:29], v[70:71]
	v_cvt_pk_bf16_f32 v32, v32, v33
	v_cvt_pk_bf16_f32 v33, v34, v35
	v_cvt_pk_bf16_f32 v34, v28, v29
	v_pk_mul_f32 v[28:29], v[30:31], v[24:25] op_sel_hi:[1,0]
	s_nop 0
	v_pk_mul_f32 v[28:29], v[28:29], v[202:203]
	s_nop 0
	v_pk_mul_f32 v[26:27], v[28:29], v[26:27]
	s_nop 0
	v_cvt_pk_bf16_f32 v35, v26, v27
	global_store_dwordx4 v[64:65], v[32:35], off offset:16
	s_nop 0
	s_waitcnt vmcnt(4)
	v_pk_mul_f32 v[12:13], v[12:13], v[208:209]
	s_nop 0
	v_pk_mul_f32 v[16:17], v[16:17], v[212:213]
	v_lshlrev_b32_e32 v30, 16, v220
	v_and_b32_e32 v31, 0xffff0000, v220
	v_pk_mul_f32 v[18:19], v[18:19], v[214:215]
	v_lshlrev_b32_e32 v20, 16, v221
	v_and_b32_e32 v21, 0xffff0000, v221
	v_pk_mul_f32 v[16:17], v[16:17], v[30:31]
	v_pk_mul_f32 v[18:19], v[18:19], v[20:21]
	v_cvt_pk_bf16_f32 v16, v16, v17
	v_cvt_pk_bf16_f32 v17, v18, v19
	v_lshlrev_b32_e32 v18, 16, v222
	v_and_b32_e32 v19, 0xffff0000, v222
	v_pk_mul_f32 v[12:13], v[12:13], v[18:19]
	s_nop 0
	v_cvt_pk_bf16_f32 v18, v12, v13
	v_pk_mul_f32 v[12:13], v[14:15], v[24:25] op_sel_hi:[1,0]
	v_lshlrev_b32_e32 v14, 16, v223
	v_pk_mul_f32 v[12:13], v[12:13], v[210:211]
	v_and_b32_e32 v15, 0xffff0000, v223
	v_pk_mul_f32 v[12:13], v[12:13], v[14:15]
	s_nop 0
	v_cvt_pk_bf16_f32 v19, v12, v13
	global_store_dwordx4 v[64:65], v[16:19], off offset:32
	s_nop 0
	s_waitcnt vmcnt(3)
	v_pk_mul_f32 v[0:1], v[0:1], v[236:237]
	s_nop 0
	v_pk_mul_f32 v[4:5], v[4:5], v[240:241]
	v_lshlrev_b32_e32 v16, 16, v216
	v_and_b32_e32 v17, 0xffff0000, v216
	v_pk_mul_f32 v[6:7], v[6:7], v[242:243]
	v_lshlrev_b32_e32 v8, 16, v217
	v_and_b32_e32 v9, 0xffff0000, v217
	v_pk_mul_f32 v[4:5], v[4:5], v[16:17]
	v_pk_mul_f32 v[6:7], v[6:7], v[8:9]
	v_cvt_pk_bf16_f32 v4, v4, v5
	v_cvt_pk_bf16_f32 v5, v6, v7
	v_lshlrev_b32_e32 v6, 16, v218
	v_and_b32_e32 v7, 0xffff0000, v218
	v_pk_mul_f32 v[0:1], v[0:1], v[6:7]
	s_nop 0
	v_cvt_pk_bf16_f32 v6, v0, v1
	v_pk_mul_f32 v[0:1], v[2:3], v[24:25] op_sel_hi:[1,0]
	v_lshlrev_b32_e32 v2, 16, v219
	v_pk_mul_f32 v[0:1], v[0:1], v[238:239]
	v_and_b32_e32 v3, 0xffff0000, v219
	v_pk_mul_f32 v[0:1], v[0:1], v[2:3]
	s_nop 0
	v_cvt_pk_bf16_f32 v7, v0, v1
	global_store_dwordx4 v[64:65], v[4:7], off offset:48
	s_cbranch_scc1 .LBB0_425
